# S5 scan phase with equal wave priorities (static lead raise suspended for that phase)
# baseline (speedup 1.0000x reference)
_Z6mk_fwd6Params:
	s_load_dwordx2 s[42:43], s[0:1], 0xe8
	s_add_u32 s8, s0, 0xe8
	v_and_b32_e32 v1, 0x3ff, v0
	s_addc_u32 s9, s1, 0
	v_readfirstlane_b32 s68, v1
	s_nop 3
	s_lshr_b32 s98, s68, 6
	v_writelane_b32 v255, s98, 13
	s_cmp_lt_u32 s98, 4
	s_cbranch_scc0 .Lprio_static_done
	s_setprio 1

.LBB0_790:
	s_or_b64 exec, exec, s[8:9]
	s_lshr_b32 s6, s68, 8
	s_lshl_b32 s7, s2, 1
	s_waitcnt lgkmcnt(0)
	s_barrier
	v_mbcnt_lo_u32_b32 v0, -1, 0
	v_mbcnt_hi_u32_b32 v0, -1, v0
	s_add_i32 s46, s6, s7
	v_add_u32_e32 v0, s3, v0
	s_mov_b64 s[8:9], s[0:1]
	s_cmpk_gt_i32 s46, 0x1ff
	s_cbranch_scc1 .LBB0_881
	s_setprio 0
	s_and_b32 s100, s46, 0x7f
	v_mbcnt_lo_u32_b32 v184, -1, 0
	v_mbcnt_hi_u32_b32 v184, -1, v184
	s_lshl_b32 s101, s100, 12
	v_lshl_add_u32 v185, v184, 6, s101
	s_lshl_b32 s101, s100, 8
	v_lshl_add_u32 v186, v184, 2, s101
	s_lshl_b32 s101, s100, 6
	v_and_b32_e32 v187, 15, v184
	v_lshl_add_u32 v187, v187, 2, s101
	s_lshl_b32 s101, s100, 2
	v_mov_b32_e32 v188, s101
	s_load_dwordx2 s[98:99], s[0:1], 0x80
	s_waitcnt lgkmcnt(0)
	global_load_dword v189, v185, s[98:99]
	s_load_dwordx2 s[98:99], s[0:1], 0x88
	s_waitcnt lgkmcnt(0)
	global_load_dword v190, v185, s[98:99]
	s_load_dwordx2 s[98:99], s[0:1], 0x90
	s_waitcnt lgkmcnt(0)
	global_load_dword v191, v185, s[98:99]
	s_load_dwordx2 s[98:99], s[0:1], 0x98
	s_waitcnt lgkmcnt(0)
	global_load_dword v192, v185, s[98:99]
	s_load_dwordx2 s[98:99], s[0:1], 0x68
	s_waitcnt lgkmcnt(0)
	global_load_dword v193, v186, s[98:99]
	s_load_dwordx2 s[98:99], s[0:1], 0x70
	s_waitcnt lgkmcnt(0)
	global_load_dword v194, v186, s[98:99]
	s_load_dwordx2 s[98:99], s[0:1], 0xa0
	s_waitcnt lgkmcnt(0)
	global_load_dword v195, v187, s[98:99]
	s_load_dwordx2 s[98:99], s[0:1], 0x78
	s_waitcnt lgkmcnt(0)
	global_load_dword v196, v188, s[98:99]
	s_load_dwordx2 s[52:53], s[8:9], 0xe0
	v_and_b32_e32 v117, 63, v0
	v_or_b32_e32 v5, 48, v117
	v_mul_u32_u24_e32 v142, 0x50, v5
	v_or_b32_e32 v5, 0x70, v117
	s_waitcnt lgkmcnt(0)
	s_add_u32 s56, s52, 0x11800000
	s_addc_u32 s57, s53, 0
	s_add_u32 s58, s52, 0x17000000
	s_addc_u32 s59, s53, 0
	s_lshl_b32 s8, s69, 9
	s_add_i32 s30, 0, 0x20800
	s_and_b32 s8, s8, 0xfffff800
	s_mulk_i32 s69, 0x4100
	s_bfe_u32 s85, s68, 0x20006
	s_add_i32 s12, s30, s8
	s_add_i32 s86, s69, 0
	s_cmp_lg_u32 s85, 3
	v_mul_u32_u24_e32 v143, 0x50, v5
	v_bfe_u32 v5, v0, 3, 3
	v_bfe_u32 v1, v0, 4, 2
	s_cselect_b64 s[60:61], -1, 0
	s_lshl_b32 s87, s85, 9
	v_and_b32_e32 v144, 6, v5
	v_lshl_add_u32 v12, v5, 4, s86
	v_lshlrev_b32_e32 v146, 2, v5
	v_or_b32_e32 v5, 8, v5
	v_and_b32_e32 v136, 15, v0
	v_lshlrev_b32_e32 v116, 3, v1
	v_mov_b32_e32 v9, s86
	s_movk_i32 s13, 0x110
	v_lshl_add_u32 v13, v5, 4, s86
	v_lshlrev_b32_e32 v147, 2, v5
	s_add_i32 s12, s12, s87
	v_lshlrev_b32_e32 v5, 3, v117
	v_cmp_gt_u32_e64 s[8:9], 32, v117
	v_lshlrev_b32_e32 v7, 2, v117
	v_add_u32_e32 v148, s12, v5
	s_cmp_lg_u32 s85, 0
	v_mad_u32_u24 v150, v136, s13, v9
	s_movk_i32 s12, 0xfef2
	v_cmp_eq_u32_e32 vcc, v116, v136
	v_or_b32_e32 v19, 1, v116
	v_and_b32_e32 v6, 60, v7
	s_cselect_b64 s[62:63], -1, 0
	v_add_u32_e32 v149, s86, v7
	v_mad_i32_i24 v7, v136, s12, v150
	s_and_b64 s[12:13], s[8:9], vcc
	v_cmp_eq_u32_e32 vcc, v19, v136
	v_or_b32_e32 v19, 2, v116
	s_and_b64 s[14:15], s[8:9], vcc
	v_cmp_eq_u32_e32 vcc, v19, v136
	v_or_b32_e32 v19, 3, v116
	s_and_b64 s[16:17], s[8:9], vcc
	v_cmp_eq_u32_e32 vcc, v19, v136
	v_or_b32_e32 v19, 4, v116
	s_and_b64 s[18:19], s[8:9], vcc
	v_cmp_eq_u32_e32 vcc, v19, v136
	v_or_b32_e32 v19, 5, v116
	s_and_b64 s[20:21], s[8:9], vcc
	v_cmp_eq_u32_e32 vcc, v19, v136
	v_or_b32_e32 v19, 6, v116
	v_writelane_b32 v255, s91, 12
	v_lshlrev_b32_e32 v2, 6, v136
	v_lshlrev_b32_e32 v4, 3, v0
	v_and_b32_e32 v11, 7, v0
	v_and_b32_e32 v14, 0x1e0, v5
	s_and_b64 s[22:23], s[8:9], vcc
	v_cmp_eq_u32_e32 vcc, v19, v136
	v_or_b32_e32 v19, 7, v116
	s_lshl_b32 s34, s6, 4
	s_add_i32 s91, s6, s7
	s_lshl_b32 s6, s6, 11
	v_mov_b32_e32 v119, 0
	v_lshl_or_b32 v3, v1, 2, v2
	v_and_b32_e32 v2, 8, v116
	v_and_b32_e32 v4, 8, v4
	v_and_b32_e32 v138, 48, v0
	v_lshlrev_b32_e32 v145, 1, v1
	v_lshl_add_u32 v10, v6, 2, s86
	v_mul_u32_u24_e32 v1, 0x110, v1
	v_lshlrev_b32_e32 v8, 3, v11
	v_mul_u32_u24_e32 v11, 0x440, v11
	v_mul_u32_u24_e32 v9, 12, v117
	v_and_b32_e32 v15, 0x180, v5
	v_or_b32_e32 v16, 0x60, v14
	v_or_b32_e32 v17, 0x260, v14
	v_or_b32_e32 v18, 0x460, v14
	v_or_b32_e32 v14, 0x660, v14
	s_and_b64 s[24:25], s[8:9], vcc
	v_cmp_eq_u32_e32 vcc, v19, v136
	v_and_b32_e32 v118, 16, v0
	s_lshl_b32 s31, s2, 5
	s_add_i32 s30, s30, s6
	s_mov_b32 s55, 0
	v_bfe_u32 v137, v0, 1, 5
	v_cmp_lt_u32_e64 s[10:11], 31, v117
	v_add_u32_e32 v139, s86, v138
	v_mul_u32_u24_e32 v140, 0x50, v117
	v_mul_u32_u24_e32 v141, 0x50, v136
	s_and_b64 s[26:27], s[8:9], vcc
	s_lshl_b32 s88, s42, 1
	v_lshl_add_u64 v[120:121], s[52:53], 0, v[118:119]
	v_or_b32_e32 v151, s87, v136
	s_add_i32 s89, s31, s34
	s_lshl_b32 s90, s42, 5
	v_add_u32_e32 v152, s30, v5
	s_mov_b32 s92, 0x3fb8aa3b
	s_brev_b32 s93, 18
	s_mov_b32 s94, 0xfe5163ab
	s_mov_b32 s95, 0x3c439041
	s_mov_b32 s96, 0xdb629599
	s_mov_b32 s97, 0xf534ddc0
	s_mov_b32 s81, 0xfc2757d1
	s_mov_b32 s82, 0x4e441529
	s_mov_b32 s83, 0xa2f9836e
	s_mov_b32 s72, 0x3fc90fda
	s_mov_b32 s48, 0x3f22f983
	s_mov_b32 s49, 0xbfc90fda
	s_mov_b32 s6, 0xc2ce8ed0
	s_mov_b32 s7, 0x42b17218
	s_movk_i32 s44, 0x1f8
	v_mov_b32_e32 v153, 0x3c0881c4
	v_mov_b32_e32 v154, 0xbab64f3b
	s_brev_b32 s45, 1
	v_lshlrev_b32_e32 v155, 2, v3
	v_lshlrev_b32_e32 v122, 1, v2
	v_lshlrev_b32_e32 v118, 2, v6
	v_add_u32_e32 v156, v10, v1
	v_lshlrev_b32_e32 v124, 1, v8
	v_add_u32_e32 v157, v12, v11
	v_add_u32_e32 v158, v13, v11
	v_lshlrev_b32_e32 v126, 1, v4
	v_add_u32_e32 v159, v149, v9
	v_add_u32_e32 v160, v7, v15
	v_add_u32_e32 v161, v7, v16
	v_add_u32_e32 v162, v7, v17
	v_add_u32_e32 v163, v7, v18
	v_add_u32_e32 v164, v7, v14
	v_not_b32_e32 v165, 63
	v_not_b32_e32 v166, 31
	v_mov_b32_e32 v167, 0x7f800000
	v_mov_b32_e32 v168, 0x7fc00000
	s_mov_b32 s84, s46
	s_branch .LBB0_793

.LBB0_881:
	v_readlane_b32 s98, v255, 13
	s_nop 3
	s_cmp_lt_u32 s98, 4
	s_cbranch_scc0 .Lprio_scan_done
	s_setprio 1
